# safe + peeled first K-tile waits count only newer loads (vmcnt 10/8 instead of 18..32): robust if store acks overtake older tile loads
# speedup vs baseline: 1.0018x; 1.0018x over previous
; #define PG8_STAGE(bufoff, gbase, voff) do { _Pragma("unroll") for (int _i = 0; _i < 2; ++_i) \
;         __builtin_amdgcn_global_load_lds((const unsigned*)((const char*)(gbase) + (voff)[_i]), (PG8_LAS unsigned*)(lds + (bufoff) + ldsw + _i * 8192), 16, 0, 0); } while (0)
; #define PG8_LDA(dst, b, h) do { _Pragma("unroll") for (int m = 0; m < 4; ++m) _Pragma("unroll") for (int k = 0; k < 2; ++k) dst[m][k] = *(const PG8_LAS bf16x8*)(lds + PG8_SA(b, h) + aoff + m * 2048 + k * 1024); } while (0)
; #define PG8_LDB(dst, b, h) do { _Pragma("unroll") for (int n = 0; n < 2; ++n) _Pragma("unroll") for (int k = 0; k < 2; ++k) dst[n][k] = *(const PG8_LAS bf16x8*)(lds + PG8_SB(b, h) + boff + n * 2048 + k * 1024); } while (0)
; #define PG8_MMA(ai, bj, At, Bt) do { __builtin_amdgcn_s_setprio(1); _Pragma("unroll") for (int m = 0; m < 4; ++m) _Pragma("unroll") for (int n = 0; n < 2; ++n) _Pragma("unroll") for (int k = 0; k < 2; ++k) \
;         acc[ai][bj][m][n] = __builtin_amdgcn_mfma_f32_16x16x32_bf16(Bt[n][k], At[m][k], acc[ai][bj][m][n], 0, 0, 0); __builtin_amdgcn_s_setprio(0); } while (0)
; #define PG8_WAIT_V(n) asm volatile("s_waitcnt vmcnt(" #n ")" ::: "memory")
; #define PG8_WAIT_L(n) asm volatile("s_waitcnt lgkmcnt(" #n ")" ::: "memory")
; template <class Epi, class Sched, bool ALIGN_EPI = false, bool SP2 = false>
; __device__ __forceinline__ void gemm_phase(PG8_LAS unsigned char* lds, const Gemm g, const Sched& S, const Epi& E) {
;     ...
;             const bool last = (t == nt - 2);
;             const char* a1 = cA + (size_t)(t + 1) * kstep;
;             const char* a2 = last ? nA : cA + (size_t)(t + 2) * kstep; const char* b2 = last ? nB : cB + (size_t)(t + 2) * kstep;
;             const char* a3 = a2 + kstep; const char* b3 = b2 + kstep;
;             if (last && has_next) S.a_ready(nxt);
;             if constexpr (SP2) {
;             PG8_LDB(B0, 0, 0); PG8_LDB(B1, 0, 1); PG8_SCHED; PG8_LDA(At, 0, 0); PG8_STAGE(PG8_SA(1, 1), a1 + hstep, voffA);
;             PG8_WAIT_V(8); PG8_WAIT_L(0); PG8_BAR; PG8_MMA(0, 0, At, B0); PG8_MMA(0, 1, At, B1); PG8_BAR; PG8_SCHED;
;             PG8_LDA(At, 0, 1); PG8_STAGE(PG8_SB(0, 0), b2, voffB); PG8_STAGE(PG8_SB(0, 1), b2 + hstep, voffB); PG8_STAGE(PG8_SA(0, 0), a2, voffA);
;             PG8_WAIT_V(8); PG8_WAIT_L(0); PG8_BAR; PG8_MMA(1, 0, At, B0); PG8_MMA(1, 1, At, B1); PG8_BAR; PG8_SCHED;
.Lpeel_g1o:
	s_add_u32 s5, s44, 0xfffc0080
	s_addc_u32 s8, s45, -1
	s_add_i32 s10, 0, 0x10000
	s_cmp_eq_u32 s76, 12
	s_cselect_b32 s67, s26, s8
	s_cselect_b32 s66, s27, s5
	v_add_u32_e32 v154, s10, v157
	s_cselect_b32 s65, s36, s59
	s_cselect_b32 s64, s39, s57
	s_add_i32 s5, 0, 0x14000
	ds_read_b128 v[162:165], v154
	ds_read_b128 v[166:169], v154 offset:1024
	ds_read_b128 v[170:173], v154 offset:2048
	ds_read_b128 v[174:177], v154 offset:3072
	v_add_u32_e32 v154, s5, v157
	ds_read_b128 v[178:181], v154
	ds_read_b128 v[182:185], v154 offset:1024
	ds_read_b128 v[186:189], v154 offset:2048
	ds_read_b128 v[190:193], v154 offset:3072
	v_lshl_add_u64 v[194:195], s[44:45], 0, v[140:141]
	s_add_i32 m0, s69, 0xc000
	ds_read_b128 v[200:203], v161
	ds_read_b128 v[204:207], v161 offset:1024
	ds_read_b128 v[208:211], v161 offset:2048
	ds_read_b128 v[212:215], v161 offset:3072
	ds_read_b128 v[216:219], v161 offset:4096
	ds_read_b128 v[220:223], v161 offset:5120
	ds_read_b128 v[224:227], v161 offset:6144
	ds_read_b128 v[228:231], v161 offset:7168
	global_load_lds_dwordx4 v[194:195], off
	v_lshl_add_u64 v[194:195], s[44:45], 0, v[138:139]
	s_add_i32 m0, s69, 0xe000
	s_nop 0
	global_load_lds_dwordx4 v[194:195], off
	s_waitcnt vmcnt(10)
	s_waitcnt lgkmcnt(0)
	s_barrier
	s_setprio 1
	s_waitcnt lgkmcnt(0)
	v_mfma_f32_16x16x32_bf16 v[124:127], v[162:165], v[200:203], 0
	v_mfma_f32_16x16x32_bf16 v[120:123], v[170:173], v[200:203], 0
	v_mfma_f32_16x16x32_bf16 v[108:111], v[162:165], v[208:211], 0
	v_mfma_f32_16x16x32_bf16 v[104:107], v[170:173], v[208:211], 0
	v_mfma_f32_16x16x32_bf16 v[92:95], v[162:165], v[216:219], 0
	v_mfma_f32_16x16x32_bf16 v[88:91], v[170:173], v[216:219], 0
	v_mfma_f32_16x16x32_bf16 v[76:79], v[162:165], v[224:227], 0
	v_mfma_f32_16x16x32_bf16 v[72:75], v[170:173], v[224:227], 0
	v_mfma_f32_16x16x32_bf16 v[124:127], v[166:169], v[204:207], v[124:127]
	v_mfma_f32_16x16x32_bf16 v[120:123], v[174:177], v[204:207], v[120:123]
	v_mfma_f32_16x16x32_bf16 v[108:111], v[166:169], v[212:215], v[108:111]
	v_mfma_f32_16x16x32_bf16 v[104:107], v[174:177], v[212:215], v[104:107]
	v_mfma_f32_16x16x32_bf16 v[92:95], v[166:169], v[220:223], v[92:95]
	v_mfma_f32_16x16x32_bf16 v[88:91], v[174:177], v[220:223], v[88:91]
	v_mfma_f32_16x16x32_bf16 v[76:79], v[166:169], v[228:231], v[76:79]
	v_mfma_f32_16x16x32_bf16 v[72:75], v[174:177], v[228:231], v[72:75]
	s_setprio 0
	s_setprio 1
	v_mfma_f32_16x16x32_bf16 v[116:119], v[178:181], v[200:203], 0
	v_mfma_f32_16x16x32_bf16 v[112:115], v[186:189], v[200:203], 0
	v_mfma_f32_16x16x32_bf16 v[100:103], v[178:181], v[208:211], 0
	v_mfma_f32_16x16x32_bf16 v[96:99], v[186:189], v[208:211], 0
	v_mfma_f32_16x16x32_bf16 v[84:87], v[178:181], v[216:219], 0
	v_mfma_f32_16x16x32_bf16 v[80:83], v[186:189], v[216:219], 0
	v_mfma_f32_16x16x32_bf16 v[68:71], v[178:181], v[224:227], 0
	v_mfma_f32_16x16x32_bf16 v[64:67], v[186:189], v[224:227], 0
	v_mfma_f32_16x16x32_bf16 v[116:119], v[182:185], v[204:207], v[116:119]
	v_mfma_f32_16x16x32_bf16 v[112:115], v[190:193], v[204:207], v[112:115]
	v_mfma_f32_16x16x32_bf16 v[100:103], v[182:185], v[212:215], v[100:103]
	v_mfma_f32_16x16x32_bf16 v[96:99], v[190:193], v[212:215], v[96:99]
	v_mfma_f32_16x16x32_bf16 v[84:87], v[182:185], v[220:223], v[84:87]
	v_mfma_f32_16x16x32_bf16 v[80:83], v[190:193], v[220:223], v[80:83]
	v_mfma_f32_16x16x32_bf16 v[68:71], v[182:185], v[228:231], v[68:71]
	v_mfma_f32_16x16x32_bf16 v[64:67], v[190:193], v[228:231], v[64:67]
	s_setprio 0
	s_barrier
	s_add_i32 s8, s10, s68
	v_lshl_add_u64 v[194:195], s[64:65], 0, v[132:133]
	s_mov_b32 m0, s8
	ds_read_b128 v[200:203], v161 offset:16384
	ds_read_b128 v[204:207], v161 offset:17408
	ds_read_b128 v[208:211], v161 offset:18432
	ds_read_b128 v[212:215], v161 offset:19456
	ds_read_b128 v[216:219], v161 offset:20480
	ds_read_b128 v[220:223], v161 offset:21504
	ds_read_b128 v[224:227], v161 offset:22528
	ds_read_b128 v[228:231], v161 offset:23552
	global_load_lds_dwordx4 v[194:195], off
	s_add_i32 m0, s8, 0x2000
	s_add_u32 s20, s64, 0x40000
	v_lshl_add_u64 v[240:241], s[64:65], 0, v[128:129]
	s_addc_u32 s21, s65, 0
	s_add_i32 s5, s5, s68
	global_load_lds_dwordx4 v[240:241], off
	v_lshl_add_u64 v[242:243], s[20:21], 0, v[132:133]
	s_mov_b32 m0, s5
	v_lshl_add_u64 v[244:245], s[66:67], 0, v[130:131]
	global_load_lds_dwordx4 v[242:243], off
	v_lshl_add_u64 v[242:243], s[20:21], 0, v[128:129]
	s_add_i32 m0, s5, 0x2000
	s_nop 0
	global_load_lds_dwordx4 v[242:243], off
	v_lshl_add_u64 v[242:243], s[66:67], 0, v[134:135]
	s_mov_b32 m0, s69
	s_nop 0
	global_load_lds_dwordx4 v[242:243], off
	s_mov_b32 m0, s70
	s_nop 0
	global_load_lds_dwordx4 v[244:245], off
	s_waitcnt vmcnt(10)
	s_waitcnt lgkmcnt(0)
	s_barrier
	s_setprio 1
	s_waitcnt lgkmcnt(0)
	v_mfma_f32_16x16x32_bf16 v[60:63], v[162:165], v[200:203], 0
	v_mfma_f32_16x16x32_bf16 v[56:59], v[170:173], v[200:203], 0
	v_mfma_f32_16x16x32_bf16 v[44:47], v[162:165], v[208:211], 0
	v_mfma_f32_16x16x32_bf16 v[40:43], v[170:173], v[208:211], 0
	v_mfma_f32_16x16x32_bf16 v[28:31], v[162:165], v[216:219], 0
	v_mfma_f32_16x16x32_bf16 v[24:27], v[170:173], v[216:219], 0
	v_mfma_f32_16x16x32_bf16 v[12:15], v[162:165], v[224:227], 0
	v_mfma_f32_16x16x32_bf16 v[8:11], v[170:173], v[224:227], 0
	v_mfma_f32_16x16x32_bf16 v[60:63], v[166:169], v[204:207], v[60:63]
	v_mfma_f32_16x16x32_bf16 v[56:59], v[174:177], v[204:207], v[56:59]
	v_mfma_f32_16x16x32_bf16 v[44:47], v[166:169], v[212:215], v[44:47]
	v_mfma_f32_16x16x32_bf16 v[40:43], v[174:177], v[212:215], v[40:43]
	v_mfma_f32_16x16x32_bf16 v[28:31], v[166:169], v[220:223], v[28:31]
	v_mfma_f32_16x16x32_bf16 v[24:27], v[174:177], v[220:223], v[24:27]
	v_mfma_f32_16x16x32_bf16 v[12:15], v[166:169], v[228:231], v[12:15]
	v_mfma_f32_16x16x32_bf16 v[8:11], v[174:177], v[228:231], v[8:11]
	s_setprio 0
	s_setprio 1
	v_mfma_f32_16x16x32_bf16 v[52:55], v[178:181], v[200:203], 0
	v_mfma_f32_16x16x32_bf16 v[48:51], v[186:189], v[200:203], 0
	v_mfma_f32_16x16x32_bf16 v[36:39], v[178:181], v[208:211], 0
	v_mfma_f32_16x16x32_bf16 v[32:35], v[186:189], v[208:211], 0
	v_mfma_f32_16x16x32_bf16 v[20:23], v[178:181], v[216:219], 0
	v_mfma_f32_16x16x32_bf16 v[16:19], v[186:189], v[216:219], 0
	v_mfma_f32_16x16x32_bf16 v[4:7], v[178:181], v[224:227], 0
	v_mfma_f32_16x16x32_bf16 v[0:3], v[186:189], v[224:227], 0
	v_mfma_f32_16x16x32_bf16 v[52:55], v[182:185], v[204:207], v[52:55]
	v_mfma_f32_16x16x32_bf16 v[48:51], v[190:193], v[204:207], v[48:51]
	v_mfma_f32_16x16x32_bf16 v[36:39], v[182:185], v[212:215], v[36:39]
	v_mfma_f32_16x16x32_bf16 v[32:35], v[190:193], v[212:215], v[32:35]
	v_mfma_f32_16x16x32_bf16 v[20:23], v[182:185], v[220:223], v[20:23]
	v_mfma_f32_16x16x32_bf16 v[16:19], v[190:193], v[220:223], v[16:19]
	v_mfma_f32_16x16x32_bf16 v[4:7], v[182:185], v[228:231], v[4:7]
	v_mfma_f32_16x16x32_bf16 v[0:3], v[190:193], v[228:231], v[0:3]
	s_setprio 0
	s_barrier
	s_branch .Lmid_g1o

; #define PG8_STAGE(bufoff, gbase, voff) do { _Pragma("unroll") for (int _i = 0; _i < 2; ++_i) \
;         __builtin_amdgcn_global_load_lds((const unsigned*)((const char*)(gbase) + (voff)[_i]), (PG8_LAS unsigned*)(lds + (bufoff) + ldsw + _i * 8192), 16, 0, 0); } while (0)
; #define PG8_LDA(dst, b, h) do { _Pragma("unroll") for (int m = 0; m < 4; ++m) _Pragma("unroll") for (int k = 0; k < 2; ++k) dst[m][k] = *(const PG8_LAS bf16x8*)(lds + PG8_SA(b, h) + aoff + m * 2048 + k * 1024); } while (0)
; #define PG8_LDB(dst, b, h) do { _Pragma("unroll") for (int n = 0; n < 2; ++n) _Pragma("unroll") for (int k = 0; k < 2; ++k) dst[n][k] = *(const PG8_LAS bf16x8*)(lds + PG8_SB(b, h) + boff + n * 2048 + k * 1024); } while (0)
; #define PG8_MMA(ai, bj, At, Bt) do { __builtin_amdgcn_s_setprio(1); _Pragma("unroll") for (int m = 0; m < 4; ++m) _Pragma("unroll") for (int n = 0; n < 2; ++n) _Pragma("unroll") for (int k = 0; k < 2; ++k) \
;         acc[ai][bj][m][n] = __builtin_amdgcn_mfma_f32_16x16x32_bf16(Bt[n][k], At[m][k], acc[ai][bj][m][n], 0, 0, 0); __builtin_amdgcn_s_setprio(0); } while (0)
; #define PG8_WAIT_V(n) asm volatile("s_waitcnt vmcnt(" #n ")" ::: "memory")
; #define PG8_WAIT_L(n) asm volatile("s_waitcnt lgkmcnt(" #n ")" ::: "memory")
; template <class Epi, class Sched, bool ALIGN_EPI = false, bool SP2 = false>
; __device__ __forceinline__ void gemm_phase(PG8_LAS unsigned char* lds, const Gemm g, const Sched& S, const Epi& E) {
;     ...
;             const bool last = (t == nt - 2);
;             const char* a1 = cA + (size_t)(t + 1) * kstep;
;             const char* a2 = last ? nA : cA + (size_t)(t + 2) * kstep; const char* b2 = last ? nB : cB + (size_t)(t + 2) * kstep;
;             const char* a3 = a2 + kstep; const char* b3 = b2 + kstep;
;             if (last && has_next) S.a_ready(nxt);
;             if constexpr (SP2) {
;             PG8_LDB(B0, 0, 0); PG8_LDB(B1, 0, 1); PG8_SCHED; PG8_LDA(At, 0, 0); PG8_STAGE(PG8_SA(1, 1), a1 + hstep, voffA);
;             PG8_WAIT_V(8); PG8_WAIT_L(0); PG8_BAR; PG8_MMA(0, 0, At, B0); PG8_MMA(0, 1, At, B1); PG8_BAR; PG8_SCHED;
;             PG8_LDA(At, 0, 1); PG8_STAGE(PG8_SB(0, 0), b2, voffB); PG8_STAGE(PG8_SB(0, 1), b2 + hstep, voffB); PG8_STAGE(PG8_SA(0, 0), a2, voffA);
;             PG8_WAIT_V(8); PG8_WAIT_L(0); PG8_BAR; PG8_MMA(1, 0, At, B0); PG8_MMA(1, 1, At, B1); PG8_BAR; PG8_SCHED;
.Lpeel_g4:
	s_add_u32 s60, s58, 0x100
	s_addc_u32 s61, s59, 0
	s_add_i32 s5, 0, 0x10000
	s_cmp_eq_u32 s39, 40
	s_cselect_b32 s65, s1, s61
	s_cselect_b32 s64, s0, s60
	s_cselect_b32 s63, s57, s27
	s_cselect_b32 s62, s56, s26
	s_add_i32 s8, 0, 0x14000
	v_add_u32_e32 v124, s5, v240
	v_add_u32_e32 v156, s8, v240
	ds_read_b128 v[112:115], v124
	ds_read_b128 v[116:119], v124 offset:1024
	ds_read_b128 v[120:123], v124 offset:2048
	ds_read_b128 v[124:127], v124 offset:3072
	ds_read_b128 v[132:135], v156
	ds_read_b128 v[140:143], v156 offset:1024
	ds_read_b128 v[152:155], v156 offset:2048
	ds_read_b128 v[156:159], v156 offset:3072
	v_lshl_add_u64 v[214:215], s[58:59], 0, v[208:209]
	s_add_i32 m0, s67, 0xc000
	ds_read_b128 v[164:167], v242
	ds_read_b128 v[172:175], v242 offset:1024
	ds_read_b128 v[176:179], v242 offset:2048
	ds_read_b128 v[180:183], v242 offset:3072
	ds_read_b128 v[184:187], v242 offset:4096
	ds_read_b128 v[188:191], v242 offset:5120
	ds_read_b128 v[192:195], v242 offset:6144
	ds_read_b128 v[210:213], v242 offset:7168
	global_load_lds_dwordx4 v[214:215], off
	v_lshl_add_u64 v[214:215], s[58:59], 0, v[206:207]
	s_add_i32 m0, s67, 0xe000
	s_nop 0
	global_load_lds_dwordx4 v[214:215], off
	s_waitcnt vmcnt(8)
	s_waitcnt lgkmcnt(0)
	s_barrier
	s_setprio 1
	s_waitcnt lgkmcnt(0)
	v_mfma_f32_16x16x32_bf16 v[168:171], v[112:115], v[164:167], 0
	v_mfma_f32_16x16x32_bf16 v[160:163], v[120:123], v[164:167], 0
	v_mfma_f32_16x16x32_bf16 v[108:111], v[112:115], v[176:179], 0
	v_mfma_f32_16x16x32_bf16 v[104:107], v[120:123], v[176:179], 0
	v_mfma_f32_16x16x32_bf16 v[92:95], v[112:115], v[184:187], 0
	v_mfma_f32_16x16x32_bf16 v[88:91], v[120:123], v[184:187], 0
	v_mfma_f32_16x16x32_bf16 v[76:79], v[112:115], v[192:195], 0
	v_mfma_f32_16x16x32_bf16 v[72:75], v[120:123], v[192:195], 0
	v_mfma_f32_16x16x32_bf16 v[168:171], v[116:119], v[172:175], v[168:171]
	v_mfma_f32_16x16x32_bf16 v[160:163], v[124:127], v[172:175], v[160:163]
	v_mfma_f32_16x16x32_bf16 v[108:111], v[116:119], v[180:183], v[108:111]
	v_mfma_f32_16x16x32_bf16 v[104:107], v[124:127], v[180:183], v[104:107]
	v_mfma_f32_16x16x32_bf16 v[92:95], v[116:119], v[188:191], v[92:95]
	v_mfma_f32_16x16x32_bf16 v[88:91], v[124:127], v[188:191], v[88:91]
	v_mfma_f32_16x16x32_bf16 v[76:79], v[116:119], v[210:213], v[76:79]
	v_mfma_f32_16x16x32_bf16 v[72:75], v[124:127], v[210:213], v[72:75]
	s_setprio 0
	s_setprio 1
	v_mfma_f32_16x16x32_bf16 v[136:139], v[132:135], v[164:167], 0
	v_mfma_f32_16x16x32_bf16 v[128:131], v[152:155], v[164:167], 0
	v_mfma_f32_16x16x32_bf16 v[100:103], v[132:135], v[176:179], 0
	v_mfma_f32_16x16x32_bf16 v[96:99], v[152:155], v[176:179], 0
	v_mfma_f32_16x16x32_bf16 v[84:87], v[132:135], v[184:187], 0
	v_mfma_f32_16x16x32_bf16 v[80:83], v[152:155], v[184:187], 0
	v_mfma_f32_16x16x32_bf16 v[68:71], v[132:135], v[192:195], 0
	v_mfma_f32_16x16x32_bf16 v[64:67], v[152:155], v[192:195], 0
	v_mfma_f32_16x16x32_bf16 v[136:139], v[140:143], v[172:175], v[136:139]
	v_mfma_f32_16x16x32_bf16 v[128:131], v[156:159], v[172:175], v[128:131]
	v_mfma_f32_16x16x32_bf16 v[100:103], v[140:143], v[180:183], v[100:103]
	v_mfma_f32_16x16x32_bf16 v[96:99], v[156:159], v[180:183], v[96:99]
	v_mfma_f32_16x16x32_bf16 v[84:87], v[140:143], v[188:191], v[84:87]
	v_mfma_f32_16x16x32_bf16 v[80:83], v[156:159], v[188:191], v[80:83]
	v_mfma_f32_16x16x32_bf16 v[68:71], v[140:143], v[210:213], v[68:71]
	v_mfma_f32_16x16x32_bf16 v[64:67], v[156:159], v[210:213], v[64:67]
	s_setprio 0
	s_barrier
	s_add_i32 s5, s5, s66
	v_lshl_add_u64 v[214:215], s[62:63], 0, v[202:203]
	s_mov_b32 m0, s5
	ds_read_b128 v[164:167], v242 offset:16384
	ds_read_b128 v[172:175], v242 offset:17408
	ds_read_b128 v[176:179], v242 offset:18432
	ds_read_b128 v[180:183], v242 offset:19456
	ds_read_b128 v[184:187], v242 offset:20480
	ds_read_b128 v[188:191], v242 offset:21504
	ds_read_b128 v[192:195], v242 offset:22528
	ds_read_b128 v[210:213], v242 offset:23552
	global_load_lds_dwordx4 v[214:215], off
	s_add_i32 m0, s5, 0x2000
	s_add_u32 s20, s62, 0xb0000
	v_lshl_add_u64 v[216:217], s[62:63], 0, v[146:147]
	s_addc_u32 s21, s63, 0
	s_add_i32 s5, s8, s66
	global_load_lds_dwordx4 v[216:217], off
	v_lshl_add_u64 v[218:219], s[20:21], 0, v[202:203]
	s_mov_b32 m0, s5
	v_lshl_add_u64 v[220:221], s[64:65], 0, v[200:201]
	global_load_lds_dwordx4 v[218:219], off
	v_lshl_add_u64 v[218:219], s[20:21], 0, v[146:147]
	s_add_i32 m0, s5, 0x2000
	s_nop 0
	global_load_lds_dwordx4 v[218:219], off
	v_lshl_add_u64 v[218:219], s[64:65], 0, v[204:205]
	s_mov_b32 m0, s67
	s_nop 0
	global_load_lds_dwordx4 v[218:219], off
	s_mov_b32 m0, s68
	s_nop 0
	global_load_lds_dwordx4 v[220:221], off
	s_waitcnt vmcnt(8)
	s_waitcnt lgkmcnt(0)
	s_barrier
	s_setprio 1
	s_waitcnt lgkmcnt(0)
	v_mfma_f32_16x16x32_bf16 v[60:63], v[112:115], v[164:167], 0
	v_mfma_f32_16x16x32_bf16 v[56:59], v[120:123], v[164:167], 0
	v_mfma_f32_16x16x32_bf16 v[44:47], v[112:115], v[176:179], 0
	v_mfma_f32_16x16x32_bf16 v[40:43], v[120:123], v[176:179], 0
	v_mfma_f32_16x16x32_bf16 v[28:31], v[112:115], v[184:187], 0
	v_mfma_f32_16x16x32_bf16 v[24:27], v[120:123], v[184:187], 0
	v_mfma_f32_16x16x32_bf16 v[12:15], v[112:115], v[192:195], 0
	v_mfma_f32_16x16x32_bf16 v[8:11], v[120:123], v[192:195], 0
	v_mfma_f32_16x16x32_bf16 v[60:63], v[116:119], v[172:175], v[60:63]
	v_mfma_f32_16x16x32_bf16 v[56:59], v[124:127], v[172:175], v[56:59]
	v_mfma_f32_16x16x32_bf16 v[44:47], v[116:119], v[180:183], v[44:47]
	v_mfma_f32_16x16x32_bf16 v[40:43], v[124:127], v[180:183], v[40:43]
	v_mfma_f32_16x16x32_bf16 v[28:31], v[116:119], v[188:191], v[28:31]
	v_mfma_f32_16x16x32_bf16 v[24:27], v[124:127], v[188:191], v[24:27]
	v_mfma_f32_16x16x32_bf16 v[12:15], v[116:119], v[210:213], v[12:15]
	v_mfma_f32_16x16x32_bf16 v[8:11], v[124:127], v[210:213], v[8:11]
	s_setprio 0
	s_setprio 1
	v_mfma_f32_16x16x32_bf16 v[52:55], v[132:135], v[164:167], 0
	v_mfma_f32_16x16x32_bf16 v[48:51], v[152:155], v[164:167], 0
	v_mfma_f32_16x16x32_bf16 v[36:39], v[132:135], v[176:179], 0
	v_mfma_f32_16x16x32_bf16 v[32:35], v[152:155], v[176:179], 0
	v_mfma_f32_16x16x32_bf16 v[20:23], v[132:135], v[184:187], 0
	v_mfma_f32_16x16x32_bf16 v[16:19], v[152:155], v[184:187], 0
	v_mfma_f32_16x16x32_bf16 v[4:7], v[132:135], v[192:195], 0
	v_mfma_f32_16x16x32_bf16 v[0:3], v[152:155], v[192:195], 0
	v_mfma_f32_16x16x32_bf16 v[52:55], v[140:143], v[172:175], v[52:55]
	v_mfma_f32_16x16x32_bf16 v[48:51], v[156:159], v[172:175], v[48:51]
	v_mfma_f32_16x16x32_bf16 v[36:39], v[140:143], v[180:183], v[36:39]
	v_mfma_f32_16x16x32_bf16 v[32:35], v[156:159], v[180:183], v[32:35]
	v_mfma_f32_16x16x32_bf16 v[20:23], v[140:143], v[188:191], v[20:23]
	v_mfma_f32_16x16x32_bf16 v[16:19], v[156:159], v[188:191], v[16:19]
	v_mfma_f32_16x16x32_bf16 v[4:7], v[140:143], v[210:213], v[4:7]
	v_mfma_f32_16x16x32_bf16 v[0:3], v[156:159], v[210:213], v[0:3]
	s_setprio 0
	s_barrier
	s_branch .Lmid_g4

; #define PG8_STAGE(bufoff, gbase, voff) do { _Pragma("unroll") for (int _i = 0; _i < 2; ++_i) \
;         __builtin_amdgcn_global_load_lds((const unsigned*)((const char*)(gbase) + (voff)[_i]), (PG8_LAS unsigned*)(lds + (bufoff) + ldsw + _i * 8192), 16, 0, 0); } while (0)
; #define PG8_LDA(dst, b, h) do { _Pragma("unroll") for (int m = 0; m < 4; ++m) _Pragma("unroll") for (int k = 0; k < 2; ++k) dst[m][k] = *(const PG8_LAS bf16x8*)(lds + PG8_SA(b, h) + aoff + m * 2048 + k * 1024); } while (0)
; #define PG8_LDB(dst, b, h) do { _Pragma("unroll") for (int n = 0; n < 2; ++n) _Pragma("unroll") for (int k = 0; k < 2; ++k) dst[n][k] = *(const PG8_LAS bf16x8*)(lds + PG8_SB(b, h) + boff + n * 2048 + k * 1024); } while (0)
; #define PG8_MMA(ai, bj, At, Bt) do { __builtin_amdgcn_s_setprio(1); _Pragma("unroll") for (int m = 0; m < 4; ++m) _Pragma("unroll") for (int n = 0; n < 2; ++n) _Pragma("unroll") for (int k = 0; k < 2; ++k) \
;         acc[ai][bj][m][n] = __builtin_amdgcn_mfma_f32_16x16x32_bf16(Bt[n][k], At[m][k], acc[ai][bj][m][n], 0, 0, 0); __builtin_amdgcn_s_setprio(0); } while (0)
; #define PG8_WAIT_V(n) asm volatile("s_waitcnt vmcnt(" #n ")" ::: "memory")
; #define PG8_WAIT_L(n) asm volatile("s_waitcnt lgkmcnt(" #n ")" ::: "memory")
; template <class Epi, class Sched, bool ALIGN_EPI = false, bool SP2 = false>
; __device__ __forceinline__ void gemm_phase(PG8_LAS unsigned char* lds, const Gemm g, const Sched& S, const Epi& E) {
;     ...
;             const bool last = (t == nt - 2);
;             const char* a1 = cA + (size_t)(t + 1) * kstep;
;             const char* a2 = last ? nA : cA + (size_t)(t + 2) * kstep; const char* b2 = last ? nB : cB + (size_t)(t + 2) * kstep;
;             const char* a3 = a2 + kstep; const char* b3 = b2 + kstep;
;             if (last && has_next) S.a_ready(nxt);
;             if constexpr (SP2) {
;             PG8_LDB(B0, 0, 0); PG8_LDB(B1, 0, 1); PG8_SCHED; PG8_LDA(At, 0, 0); PG8_STAGE(PG8_SA(1, 1), a1 + hstep, voffA);
;             PG8_WAIT_V(8); PG8_WAIT_L(0); PG8_BAR; PG8_MMA(0, 0, At, B0); PG8_MMA(0, 1, At, B1); PG8_BAR; PG8_SCHED;
;             PG8_LDA(At, 0, 1); PG8_STAGE(PG8_SB(0, 0), b2, voffB); PG8_STAGE(PG8_SB(0, 1), b2 + hstep, voffB); PG8_STAGE(PG8_SA(0, 0), a2, voffA);
;             PG8_WAIT_V(8); PG8_WAIT_L(0); PG8_BAR; PG8_MMA(1, 0, At, B0); PG8_MMA(1, 1, At, B1); PG8_BAR; PG8_SCHED;
.Lpeel_g3:
	s_add_u32 s5, s58, 0xfffc0080
	s_addc_u32 s8, s59, -1
	s_add_i32 s10, 0, 0x10000
	s_cmp_eq_u32 s72, 12
	s_cselect_b32 s63, s26, s8
	s_cselect_b32 s62, s27, s5
	v_add_u32_e32 v143, s10, v157
	s_cselect_b32 s61, s36, s53
	s_cselect_b32 s60, s39, s51
	s_add_i32 s5, 0, 0x14000
	ds_read_b128 v[162:165], v143
	ds_read_b128 v[166:169], v143 offset:1024
	ds_read_b128 v[170:173], v143 offset:2048
	ds_read_b128 v[174:177], v143 offset:3072
	v_add_u32_e32 v143, s5, v157
	ds_read_b128 v[178:181], v143
	ds_read_b128 v[182:185], v143 offset:1024
	ds_read_b128 v[186:189], v143 offset:2048
	ds_read_b128 v[190:193], v143 offset:3072
	v_lshl_add_u64 v[194:195], s[58:59], 0, v[140:141]
	s_add_i32 m0, s65, 0xc000
	ds_read_b128 v[200:203], v161
	ds_read_b128 v[204:207], v161 offset:1024
	ds_read_b128 v[208:211], v161 offset:2048
	ds_read_b128 v[212:215], v161 offset:3072
	ds_read_b128 v[216:219], v161 offset:4096
	ds_read_b128 v[220:223], v161 offset:5120
	ds_read_b128 v[224:227], v161 offset:6144
	ds_read_b128 v[228:231], v161 offset:7168
	global_load_lds_dwordx4 v[194:195], off
	v_lshl_add_u64 v[194:195], s[58:59], 0, v[138:139]
	s_add_i32 m0, s65, 0xe000
	s_nop 0
	global_load_lds_dwordx4 v[194:195], off
	s_waitcnt vmcnt(10)
	s_waitcnt lgkmcnt(0)
	s_barrier
	s_setprio 1
	s_waitcnt lgkmcnt(0)
	v_mfma_f32_16x16x32_bf16 v[124:127], v[162:165], v[200:203], 0
	v_mfma_f32_16x16x32_bf16 v[120:123], v[170:173], v[200:203], 0
	v_mfma_f32_16x16x32_bf16 v[108:111], v[162:165], v[208:211], 0
	v_mfma_f32_16x16x32_bf16 v[104:107], v[170:173], v[208:211], 0
	v_mfma_f32_16x16x32_bf16 v[92:95], v[162:165], v[216:219], 0
	v_mfma_f32_16x16x32_bf16 v[88:91], v[170:173], v[216:219], 0
	v_mfma_f32_16x16x32_bf16 v[76:79], v[162:165], v[224:227], 0
	v_mfma_f32_16x16x32_bf16 v[72:75], v[170:173], v[224:227], 0
	v_mfma_f32_16x16x32_bf16 v[124:127], v[166:169], v[204:207], v[124:127]
	v_mfma_f32_16x16x32_bf16 v[120:123], v[174:177], v[204:207], v[120:123]
	v_mfma_f32_16x16x32_bf16 v[108:111], v[166:169], v[212:215], v[108:111]
	v_mfma_f32_16x16x32_bf16 v[104:107], v[174:177], v[212:215], v[104:107]
	v_mfma_f32_16x16x32_bf16 v[92:95], v[166:169], v[220:223], v[92:95]
	v_mfma_f32_16x16x32_bf16 v[88:91], v[174:177], v[220:223], v[88:91]
	v_mfma_f32_16x16x32_bf16 v[76:79], v[166:169], v[228:231], v[76:79]
	v_mfma_f32_16x16x32_bf16 v[72:75], v[174:177], v[228:231], v[72:75]
	s_setprio 0
	s_setprio 1
	v_mfma_f32_16x16x32_bf16 v[116:119], v[178:181], v[200:203], 0
	v_mfma_f32_16x16x32_bf16 v[112:115], v[186:189], v[200:203], 0
	v_mfma_f32_16x16x32_bf16 v[100:103], v[178:181], v[208:211], 0
	v_mfma_f32_16x16x32_bf16 v[96:99], v[186:189], v[208:211], 0
	v_mfma_f32_16x16x32_bf16 v[84:87], v[178:181], v[216:219], 0
	v_mfma_f32_16x16x32_bf16 v[80:83], v[186:189], v[216:219], 0
	v_mfma_f32_16x16x32_bf16 v[68:71], v[178:181], v[224:227], 0
	v_mfma_f32_16x16x32_bf16 v[64:67], v[186:189], v[224:227], 0
	v_mfma_f32_16x16x32_bf16 v[116:119], v[182:185], v[204:207], v[116:119]
	v_mfma_f32_16x16x32_bf16 v[112:115], v[190:193], v[204:207], v[112:115]
	v_mfma_f32_16x16x32_bf16 v[100:103], v[182:185], v[212:215], v[100:103]
	v_mfma_f32_16x16x32_bf16 v[96:99], v[190:193], v[212:215], v[96:99]
	v_mfma_f32_16x16x32_bf16 v[84:87], v[182:185], v[220:223], v[84:87]
	v_mfma_f32_16x16x32_bf16 v[80:83], v[190:193], v[220:223], v[80:83]
	v_mfma_f32_16x16x32_bf16 v[68:71], v[182:185], v[228:231], v[68:71]
	v_mfma_f32_16x16x32_bf16 v[64:67], v[190:193], v[228:231], v[64:67]
	s_setprio 0
	s_barrier
	s_add_i32 s8, s10, s64
	v_lshl_add_u64 v[194:195], s[60:61], 0, v[132:133]
	s_mov_b32 m0, s8
	ds_read_b128 v[200:203], v161 offset:16384
	ds_read_b128 v[204:207], v161 offset:17408
	ds_read_b128 v[208:211], v161 offset:18432
	ds_read_b128 v[212:215], v161 offset:19456
	ds_read_b128 v[216:219], v161 offset:20480
	ds_read_b128 v[220:223], v161 offset:21504
	ds_read_b128 v[224:227], v161 offset:22528
	ds_read_b128 v[228:231], v161 offset:23552
	global_load_lds_dwordx4 v[194:195], off
	s_add_i32 m0, s8, 0x2000
	s_add_u32 s20, s60, 0x40000
	v_lshl_add_u64 v[240:241], s[60:61], 0, v[128:129]
	s_addc_u32 s21, s61, 0
	s_add_i32 s5, s5, s64
	global_load_lds_dwordx4 v[240:241], off
	v_lshl_add_u64 v[242:243], s[20:21], 0, v[132:133]
	s_mov_b32 m0, s5
	v_lshl_add_u64 v[244:245], s[62:63], 0, v[130:131]
	global_load_lds_dwordx4 v[242:243], off
	v_lshl_add_u64 v[242:243], s[20:21], 0, v[128:129]
	s_add_i32 m0, s5, 0x2000
	s_nop 0
	global_load_lds_dwordx4 v[242:243], off
	v_lshl_add_u64 v[242:243], s[62:63], 0, v[134:135]
	s_mov_b32 m0, s65
	s_nop 0
	global_load_lds_dwordx4 v[242:243], off
	s_mov_b32 m0, s66
	s_nop 0
	global_load_lds_dwordx4 v[244:245], off
	s_waitcnt vmcnt(10)
	s_waitcnt lgkmcnt(0)
	s_barrier
	s_setprio 1
	s_waitcnt lgkmcnt(0)
	v_mfma_f32_16x16x32_bf16 v[60:63], v[162:165], v[200:203], 0
	v_mfma_f32_16x16x32_bf16 v[56:59], v[170:173], v[200:203], 0
	v_mfma_f32_16x16x32_bf16 v[44:47], v[162:165], v[208:211], 0
	v_mfma_f32_16x16x32_bf16 v[40:43], v[170:173], v[208:211], 0
	v_mfma_f32_16x16x32_bf16 v[28:31], v[162:165], v[216:219], 0
	v_mfma_f32_16x16x32_bf16 v[24:27], v[170:173], v[216:219], 0
	v_mfma_f32_16x16x32_bf16 v[12:15], v[162:165], v[224:227], 0
	v_mfma_f32_16x16x32_bf16 v[8:11], v[170:173], v[224:227], 0
	v_mfma_f32_16x16x32_bf16 v[60:63], v[166:169], v[204:207], v[60:63]
	v_mfma_f32_16x16x32_bf16 v[56:59], v[174:177], v[204:207], v[56:59]
	v_mfma_f32_16x16x32_bf16 v[44:47], v[166:169], v[212:215], v[44:47]
	v_mfma_f32_16x16x32_bf16 v[40:43], v[174:177], v[212:215], v[40:43]
	v_mfma_f32_16x16x32_bf16 v[28:31], v[166:169], v[220:223], v[28:31]
	v_mfma_f32_16x16x32_bf16 v[24:27], v[174:177], v[220:223], v[24:27]
	v_mfma_f32_16x16x32_bf16 v[12:15], v[166:169], v[228:231], v[12:15]
	v_mfma_f32_16x16x32_bf16 v[8:11], v[174:177], v[228:231], v[8:11]
	s_setprio 0
	s_setprio 1
	v_mfma_f32_16x16x32_bf16 v[52:55], v[178:181], v[200:203], 0
	v_mfma_f32_16x16x32_bf16 v[48:51], v[186:189], v[200:203], 0
	v_mfma_f32_16x16x32_bf16 v[36:39], v[178:181], v[208:211], 0
	v_mfma_f32_16x16x32_bf16 v[32:35], v[186:189], v[208:211], 0
	v_mfma_f32_16x16x32_bf16 v[20:23], v[178:181], v[216:219], 0
	v_mfma_f32_16x16x32_bf16 v[16:19], v[186:189], v[216:219], 0
	v_mfma_f32_16x16x32_bf16 v[4:7], v[178:181], v[224:227], 0
	v_mfma_f32_16x16x32_bf16 v[0:3], v[186:189], v[224:227], 0
	v_mfma_f32_16x16x32_bf16 v[52:55], v[182:185], v[204:207], v[52:55]
	v_mfma_f32_16x16x32_bf16 v[48:51], v[190:193], v[204:207], v[48:51]
	v_mfma_f32_16x16x32_bf16 v[36:39], v[182:185], v[212:215], v[36:39]
	v_mfma_f32_16x16x32_bf16 v[32:35], v[190:193], v[212:215], v[32:35]
	v_mfma_f32_16x16x32_bf16 v[20:23], v[182:185], v[220:223], v[20:23]
	v_mfma_f32_16x16x32_bf16 v[16:19], v[190:193], v[220:223], v[16:19]
	v_mfma_f32_16x16x32_bf16 v[4:7], v[182:185], v[228:231], v[4:7]
	v_mfma_f32_16x16x32_bf16 v[0:3], v[190:193], v[228:231], v[0:3]
	s_setprio 0
	s_barrier
	s_branch .Lmid_g3

; #define PG8_STAGE(bufoff, gbase, voff) do { _Pragma("unroll") for (int _i = 0; _i < 2; ++_i) \
;         __builtin_amdgcn_global_load_lds((const unsigned*)((const char*)(gbase) + (voff)[_i]), (PG8_LAS unsigned*)(lds + (bufoff) + ldsw + _i * 8192), 16, 0, 0); } while (0)
; #define PG8_LDA(dst, b, h) do { _Pragma("unroll") for (int m = 0; m < 4; ++m) _Pragma("unroll") for (int k = 0; k < 2; ++k) dst[m][k] = *(const PG8_LAS bf16x8*)(lds + PG8_SA(b, h) + aoff + m * 2048 + k * 1024); } while (0)
; #define PG8_LDB(dst, b, h) do { _Pragma("unroll") for (int n = 0; n < 2; ++n) _Pragma("unroll") for (int k = 0; k < 2; ++k) dst[n][k] = *(const PG8_LAS bf16x8*)(lds + PG8_SB(b, h) + boff + n * 2048 + k * 1024); } while (0)
; #define PG8_MMA(ai, bj, At, Bt) do { __builtin_amdgcn_s_setprio(1); _Pragma("unroll") for (int m = 0; m < 4; ++m) _Pragma("unroll") for (int n = 0; n < 2; ++n) _Pragma("unroll") for (int k = 0; k < 2; ++k) \
;         acc[ai][bj][m][n] = __builtin_amdgcn_mfma_f32_16x16x32_bf16(Bt[n][k], At[m][k], acc[ai][bj][m][n], 0, 0, 0); __builtin_amdgcn_s_setprio(0); } while (0)
; #define PG8_WAIT_V(n) asm volatile("s_waitcnt vmcnt(" #n ")" ::: "memory")
; #define PG8_WAIT_L(n) asm volatile("s_waitcnt lgkmcnt(" #n ")" ::: "memory")
; template <class Epi, class Sched, bool ALIGN_EPI = false, bool SP2 = false>
; __device__ __forceinline__ void gemm_phase(PG8_LAS unsigned char* lds, const Gemm g, const Sched& S, const Epi& E) {
;     ...
;             const bool last = (t == nt - 2);
;             const char* a1 = cA + (size_t)(t + 1) * kstep;
;             const char* a2 = last ? nA : cA + (size_t)(t + 2) * kstep; const char* b2 = last ? nB : cB + (size_t)(t + 2) * kstep;
;             const char* a3 = a2 + kstep; const char* b3 = b2 + kstep;
;             if (last && has_next) S.a_ready(nxt);
;             if constexpr (SP2) {
;             PG8_LDB(B0, 0, 0); PG8_LDB(B1, 0, 1); PG8_SCHED; PG8_LDA(At, 0, 0); PG8_STAGE(PG8_SA(1, 1), a1 + hstep, voffA);
;             PG8_WAIT_V(8); PG8_WAIT_L(0); PG8_BAR; PG8_MMA(0, 0, At, B0); PG8_MMA(0, 1, At, B1); PG8_BAR; PG8_SCHED;
;             PG8_LDA(At, 0, 1); PG8_STAGE(PG8_SB(0, 0), b2, voffB); PG8_STAGE(PG8_SB(0, 1), b2 + hstep, voffB); PG8_STAGE(PG8_SA(0, 0), a2, voffA);
;             PG8_WAIT_V(8); PG8_WAIT_L(0); PG8_BAR; PG8_MMA(1, 0, At, B0); PG8_MMA(1, 1, At, B1); PG8_BAR; PG8_SCHED;
.Lpeel_g2:
	s_add_u32 s5, s60, 0xfffc0080
	s_addc_u32 s8, s61, -1
	s_add_i32 s10, 0, 0x10000
	s_cmp_eq_u32 s74, 12
	s_cselect_b32 s65, s26, s8
	s_cselect_b32 s64, s27, s5
	s_cselect_b32 s63, s39, s73
	s_cselect_b32 s62, s53, s55
	s_add_i32 s5, 0, 0x14000
	v_add_u32_e32 v124, s10, v240
	v_add_u32_e32 v156, s5, v240
	ds_read_b128 v[112:115], v124
	ds_read_b128 v[116:119], v124 offset:1024
	ds_read_b128 v[120:123], v124 offset:2048
	ds_read_b128 v[124:127], v124 offset:3072
	ds_read_b128 v[136:139], v156
	ds_read_b128 v[140:143], v156 offset:1024
	ds_read_b128 v[152:155], v156 offset:2048
	ds_read_b128 v[156:159], v156 offset:3072
	v_lshl_add_u64 v[214:215], s[60:61], 0, v[208:209]
	s_add_i32 m0, s67, 0xc000
	ds_read_b128 v[164:167], v242
	ds_read_b128 v[172:175], v242 offset:1024
	ds_read_b128 v[176:179], v242 offset:2048
	ds_read_b128 v[180:183], v242 offset:3072
	ds_read_b128 v[184:187], v242 offset:4096
	ds_read_b128 v[188:191], v242 offset:5120
	ds_read_b128 v[192:195], v242 offset:6144
	ds_read_b128 v[210:213], v242 offset:7168
	global_load_lds_dwordx4 v[214:215], off
	v_lshl_add_u64 v[214:215], s[60:61], 0, v[206:207]
	s_add_i32 m0, s67, 0xe000
	s_nop 0
	global_load_lds_dwordx4 v[214:215], off
	s_waitcnt vmcnt(8)
	s_waitcnt lgkmcnt(0)
	s_barrier
	s_setprio 1
	s_waitcnt lgkmcnt(0)
	v_mfma_f32_16x16x32_bf16 v[168:171], v[112:115], v[164:167], 0
	v_mfma_f32_16x16x32_bf16 v[160:163], v[120:123], v[164:167], 0
	v_mfma_f32_16x16x32_bf16 v[108:111], v[112:115], v[176:179], 0
	v_mfma_f32_16x16x32_bf16 v[104:107], v[120:123], v[176:179], 0
	v_mfma_f32_16x16x32_bf16 v[92:95], v[112:115], v[184:187], 0
	v_mfma_f32_16x16x32_bf16 v[88:91], v[120:123], v[184:187], 0
	v_mfma_f32_16x16x32_bf16 v[76:79], v[112:115], v[192:195], 0
	v_mfma_f32_16x16x32_bf16 v[72:75], v[120:123], v[192:195], 0
	v_mfma_f32_16x16x32_bf16 v[168:171], v[116:119], v[172:175], v[168:171]
	v_mfma_f32_16x16x32_bf16 v[160:163], v[124:127], v[172:175], v[160:163]
	v_mfma_f32_16x16x32_bf16 v[108:111], v[116:119], v[180:183], v[108:111]
	v_mfma_f32_16x16x32_bf16 v[104:107], v[124:127], v[180:183], v[104:107]
	v_mfma_f32_16x16x32_bf16 v[92:95], v[116:119], v[188:191], v[92:95]
	v_mfma_f32_16x16x32_bf16 v[88:91], v[124:127], v[188:191], v[88:91]
	v_mfma_f32_16x16x32_bf16 v[76:79], v[116:119], v[210:213], v[76:79]
	v_mfma_f32_16x16x32_bf16 v[72:75], v[124:127], v[210:213], v[72:75]
	s_setprio 0
	s_setprio 1
	v_mfma_f32_16x16x32_bf16 v[132:135], v[136:139], v[164:167], 0
	v_mfma_f32_16x16x32_bf16 v[128:131], v[152:155], v[164:167], 0
	v_mfma_f32_16x16x32_bf16 v[100:103], v[136:139], v[176:179], 0
	v_mfma_f32_16x16x32_bf16 v[96:99], v[152:155], v[176:179], 0
	v_mfma_f32_16x16x32_bf16 v[84:87], v[136:139], v[184:187], 0
	v_mfma_f32_16x16x32_bf16 v[80:83], v[152:155], v[184:187], 0
	v_mfma_f32_16x16x32_bf16 v[68:71], v[136:139], v[192:195], 0
	v_mfma_f32_16x16x32_bf16 v[64:67], v[152:155], v[192:195], 0
	v_mfma_f32_16x16x32_bf16 v[132:135], v[140:143], v[172:175], v[132:135]
	v_mfma_f32_16x16x32_bf16 v[128:131], v[156:159], v[172:175], v[128:131]
	v_mfma_f32_16x16x32_bf16 v[100:103], v[140:143], v[180:183], v[100:103]
	v_mfma_f32_16x16x32_bf16 v[96:99], v[156:159], v[180:183], v[96:99]
	v_mfma_f32_16x16x32_bf16 v[84:87], v[140:143], v[188:191], v[84:87]
	v_mfma_f32_16x16x32_bf16 v[80:83], v[156:159], v[188:191], v[80:83]
	v_mfma_f32_16x16x32_bf16 v[68:71], v[140:143], v[210:213], v[68:71]
	v_mfma_f32_16x16x32_bf16 v[64:67], v[156:159], v[210:213], v[64:67]
	s_setprio 0
	s_barrier
	s_add_i32 s8, s10, s66
	v_lshl_add_u64 v[214:215], s[62:63], 0, v[202:203]
	s_mov_b32 m0, s8
	ds_read_b128 v[164:167], v242 offset:16384
	ds_read_b128 v[172:175], v242 offset:17408
	ds_read_b128 v[176:179], v242 offset:18432
	ds_read_b128 v[180:183], v242 offset:19456
	ds_read_b128 v[184:187], v242 offset:20480
	ds_read_b128 v[188:191], v242 offset:21504
	ds_read_b128 v[192:195], v242 offset:22528
	ds_read_b128 v[210:213], v242 offset:23552
	global_load_lds_dwordx4 v[214:215], off
	s_add_i32 m0, s8, 0x2000
	s_add_u32 s20, s62, 0x40000
	v_lshl_add_u64 v[216:217], s[62:63], 0, v[146:147]
	s_addc_u32 s21, s63, 0
	s_add_i32 s5, s5, s66
	global_load_lds_dwordx4 v[216:217], off
	v_lshl_add_u64 v[218:219], s[20:21], 0, v[202:203]
	s_mov_b32 m0, s5
	v_lshl_add_u64 v[220:221], s[64:65], 0, v[200:201]
	global_load_lds_dwordx4 v[218:219], off
	v_lshl_add_u64 v[218:219], s[20:21], 0, v[146:147]
	s_add_i32 m0, s5, 0x2000
	s_nop 0
	global_load_lds_dwordx4 v[218:219], off
	v_lshl_add_u64 v[218:219], s[64:65], 0, v[204:205]
	s_mov_b32 m0, s67
	s_nop 0
	global_load_lds_dwordx4 v[218:219], off
	s_mov_b32 m0, s68
	s_nop 0
	global_load_lds_dwordx4 v[220:221], off
	s_waitcnt vmcnt(8)
	s_waitcnt lgkmcnt(0)
	s_barrier
	s_setprio 1
	s_waitcnt lgkmcnt(0)
	v_mfma_f32_16x16x32_bf16 v[60:63], v[112:115], v[164:167], 0
	v_mfma_f32_16x16x32_bf16 v[56:59], v[120:123], v[164:167], 0
	v_mfma_f32_16x16x32_bf16 v[44:47], v[112:115], v[176:179], 0
	v_mfma_f32_16x16x32_bf16 v[40:43], v[120:123], v[176:179], 0
	v_mfma_f32_16x16x32_bf16 v[28:31], v[112:115], v[184:187], 0
	v_mfma_f32_16x16x32_bf16 v[24:27], v[120:123], v[184:187], 0
	v_mfma_f32_16x16x32_bf16 v[12:15], v[112:115], v[192:195], 0
	v_mfma_f32_16x16x32_bf16 v[8:11], v[120:123], v[192:195], 0
	v_mfma_f32_16x16x32_bf16 v[60:63], v[116:119], v[172:175], v[60:63]
	v_mfma_f32_16x16x32_bf16 v[56:59], v[124:127], v[172:175], v[56:59]
	v_mfma_f32_16x16x32_bf16 v[44:47], v[116:119], v[180:183], v[44:47]
	v_mfma_f32_16x16x32_bf16 v[40:43], v[124:127], v[180:183], v[40:43]
	v_mfma_f32_16x16x32_bf16 v[28:31], v[116:119], v[188:191], v[28:31]
	v_mfma_f32_16x16x32_bf16 v[24:27], v[124:127], v[188:191], v[24:27]
	v_mfma_f32_16x16x32_bf16 v[12:15], v[116:119], v[210:213], v[12:15]
	v_mfma_f32_16x16x32_bf16 v[8:11], v[124:127], v[210:213], v[8:11]
	s_setprio 0
	s_setprio 1
	v_mfma_f32_16x16x32_bf16 v[52:55], v[136:139], v[164:167], 0
	v_mfma_f32_16x16x32_bf16 v[48:51], v[152:155], v[164:167], 0
	v_mfma_f32_16x16x32_bf16 v[36:39], v[136:139], v[176:179], 0
	v_mfma_f32_16x16x32_bf16 v[32:35], v[152:155], v[176:179], 0
	v_mfma_f32_16x16x32_bf16 v[20:23], v[136:139], v[184:187], 0
	v_mfma_f32_16x16x32_bf16 v[16:19], v[152:155], v[184:187], 0
	v_mfma_f32_16x16x32_bf16 v[4:7], v[136:139], v[192:195], 0
	v_mfma_f32_16x16x32_bf16 v[0:3], v[152:155], v[192:195], 0
	v_mfma_f32_16x16x32_bf16 v[52:55], v[140:143], v[172:175], v[52:55]
	v_mfma_f32_16x16x32_bf16 v[48:51], v[156:159], v[172:175], v[48:51]
	v_mfma_f32_16x16x32_bf16 v[36:39], v[140:143], v[180:183], v[36:39]
	v_mfma_f32_16x16x32_bf16 v[32:35], v[156:159], v[180:183], v[32:35]
	v_mfma_f32_16x16x32_bf16 v[20:23], v[140:143], v[188:191], v[20:23]
	v_mfma_f32_16x16x32_bf16 v[16:19], v[156:159], v[188:191], v[16:19]
	v_mfma_f32_16x16x32_bf16 v[4:7], v[140:143], v[210:213], v[4:7]
	v_mfma_f32_16x16x32_bf16 v[0:3], v[156:159], v[210:213], v[0:3]
	s_setprio 0
	s_barrier
	s_branch .Lmid_g2

; #define PG8_STAGE(bufoff, gbase, voff) do { _Pragma("unroll") for (int _i = 0; _i < 2; ++_i) \
;         __builtin_amdgcn_global_load_lds((const unsigned*)((const char*)(gbase) + (voff)[_i]), (PG8_LAS unsigned*)(lds + (bufoff) + ldsw + _i * 8192), 16, 0, 0); } while (0)
; #define PG8_LDA(dst, b, h) do { _Pragma("unroll") for (int m = 0; m < 4; ++m) _Pragma("unroll") for (int k = 0; k < 2; ++k) dst[m][k] = *(const PG8_LAS bf16x8*)(lds + PG8_SA(b, h) + aoff + m * 2048 + k * 1024); } while (0)
; #define PG8_LDB(dst, b, h) do { _Pragma("unroll") for (int n = 0; n < 2; ++n) _Pragma("unroll") for (int k = 0; k < 2; ++k) dst[n][k] = *(const PG8_LAS bf16x8*)(lds + PG8_SB(b, h) + boff + n * 2048 + k * 1024); } while (0)
; #define PG8_MMA(ai, bj, At, Bt) do { __builtin_amdgcn_s_setprio(1); _Pragma("unroll") for (int m = 0; m < 4; ++m) _Pragma("unroll") for (int n = 0; n < 2; ++n) _Pragma("unroll") for (int k = 0; k < 2; ++k) \
;         acc[ai][bj][m][n] = __builtin_amdgcn_mfma_f32_16x16x32_bf16(Bt[n][k], At[m][k], acc[ai][bj][m][n], 0, 0, 0); __builtin_amdgcn_s_setprio(0); } while (0)
; #define PG8_WAIT_V(n) asm volatile("s_waitcnt vmcnt(" #n ")" ::: "memory")
; #define PG8_WAIT_L(n) asm volatile("s_waitcnt lgkmcnt(" #n ")" ::: "memory")
; template <class Epi, class Sched, bool ALIGN_EPI = false, bool SP2 = false>
; __device__ __forceinline__ void gemm_phase(PG8_LAS unsigned char* lds, const Gemm g, const Sched& S, const Epi& E) {
;     ...
;             const bool last = (t == nt - 2);
;             const char* a1 = cA + (size_t)(t + 1) * kstep;
;             const char* a2 = last ? nA : cA + (size_t)(t + 2) * kstep; const char* b2 = last ? nB : cB + (size_t)(t + 2) * kstep;
;             const char* a3 = a2 + kstep; const char* b3 = b2 + kstep;
;             if (last && has_next) S.a_ready(nxt);
;             if constexpr (SP2) {
;             PG8_LDB(B0, 0, 0); PG8_LDB(B1, 0, 1); PG8_SCHED; PG8_LDA(At, 0, 0); PG8_STAGE(PG8_SA(1, 1), a1 + hstep, voffA);
;             PG8_WAIT_V(8); PG8_WAIT_L(0); PG8_BAR; PG8_MMA(0, 0, At, B0); PG8_MMA(0, 1, At, B1); PG8_BAR; PG8_SCHED;
;             PG8_LDA(At, 0, 1); PG8_STAGE(PG8_SB(0, 0), b2, voffB); PG8_STAGE(PG8_SB(0, 1), b2 + hstep, voffB); PG8_STAGE(PG8_SA(0, 0), a2, voffA);
;             PG8_WAIT_V(8); PG8_WAIT_L(0); PG8_BAR; PG8_MMA(1, 0, At, B0); PG8_MMA(1, 1, At, B1); PG8_BAR; PG8_SCHED;
.Lpeel_g1e:
	s_add_u32 s8, s44, 0xfffc0080
	s_addc_u32 s10, s45, -1
	s_add_i32 s12, 0, 0x10000
	s_cmp_eq_u32 s69, 12
	s_cselect_b32 s57, s4, s10
	s_cselect_b32 s56, s26, s8
	v_add_u32_e32 v154, s12, v157
	s_cselect_b32 s55, s27, s49
	s_cselect_b32 s54, s36, s47
	s_add_i32 s8, 0, 0x14000
	ds_read_b128 v[162:165], v154
	ds_read_b128 v[166:169], v154 offset:1024
	ds_read_b128 v[170:173], v154 offset:2048
	ds_read_b128 v[174:177], v154 offset:3072
	v_add_u32_e32 v154, s8, v157
	ds_read_b128 v[178:181], v154
	ds_read_b128 v[182:185], v154 offset:1024
	ds_read_b128 v[186:189], v154 offset:2048
	ds_read_b128 v[190:193], v154 offset:3072
	v_lshl_add_u64 v[194:195], s[44:45], 0, v[140:141]
	s_add_i32 m0, s58, 0xc000
	ds_read_b128 v[200:203], v161
	ds_read_b128 v[204:207], v161 offset:1024
	ds_read_b128 v[208:211], v161 offset:2048
	ds_read_b128 v[212:215], v161 offset:3072
	ds_read_b128 v[216:219], v161 offset:4096
	ds_read_b128 v[220:223], v161 offset:5120
	ds_read_b128 v[224:227], v161 offset:6144
	ds_read_b128 v[228:231], v161 offset:7168
	global_load_lds_dwordx4 v[194:195], off
	v_lshl_add_u64 v[194:195], s[44:45], 0, v[138:139]
	s_add_i32 m0, s58, 0xe000
	s_nop 0
	global_load_lds_dwordx4 v[194:195], off
	s_waitcnt vmcnt(10)
	s_waitcnt lgkmcnt(0)
	s_barrier
	s_setprio 1
	s_waitcnt lgkmcnt(0)
	v_mfma_f32_16x16x32_bf16 v[124:127], v[162:165], v[200:203], 0
	v_mfma_f32_16x16x32_bf16 v[120:123], v[170:173], v[200:203], 0
	v_mfma_f32_16x16x32_bf16 v[108:111], v[162:165], v[208:211], 0
	v_mfma_f32_16x16x32_bf16 v[104:107], v[170:173], v[208:211], 0
	v_mfma_f32_16x16x32_bf16 v[92:95], v[162:165], v[216:219], 0
	v_mfma_f32_16x16x32_bf16 v[88:91], v[170:173], v[216:219], 0
	v_mfma_f32_16x16x32_bf16 v[76:79], v[162:165], v[224:227], 0
	v_mfma_f32_16x16x32_bf16 v[72:75], v[170:173], v[224:227], 0
	v_mfma_f32_16x16x32_bf16 v[124:127], v[166:169], v[204:207], v[124:127]
	v_mfma_f32_16x16x32_bf16 v[120:123], v[174:177], v[204:207], v[120:123]
	v_mfma_f32_16x16x32_bf16 v[108:111], v[166:169], v[212:215], v[108:111]
	v_mfma_f32_16x16x32_bf16 v[104:107], v[174:177], v[212:215], v[104:107]
	v_mfma_f32_16x16x32_bf16 v[92:95], v[166:169], v[220:223], v[92:95]
	v_mfma_f32_16x16x32_bf16 v[88:91], v[174:177], v[220:223], v[88:91]
	v_mfma_f32_16x16x32_bf16 v[76:79], v[166:169], v[228:231], v[76:79]
	v_mfma_f32_16x16x32_bf16 v[72:75], v[174:177], v[228:231], v[72:75]
	s_setprio 0
	s_setprio 1
	v_mfma_f32_16x16x32_bf16 v[116:119], v[178:181], v[200:203], 0
	v_mfma_f32_16x16x32_bf16 v[112:115], v[186:189], v[200:203], 0
	v_mfma_f32_16x16x32_bf16 v[100:103], v[178:181], v[208:211], 0
	v_mfma_f32_16x16x32_bf16 v[96:99], v[186:189], v[208:211], 0
	v_mfma_f32_16x16x32_bf16 v[84:87], v[178:181], v[216:219], 0
	v_mfma_f32_16x16x32_bf16 v[80:83], v[186:189], v[216:219], 0
	v_mfma_f32_16x16x32_bf16 v[68:71], v[178:181], v[224:227], 0
	v_mfma_f32_16x16x32_bf16 v[64:67], v[186:189], v[224:227], 0
	v_mfma_f32_16x16x32_bf16 v[116:119], v[182:185], v[204:207], v[116:119]
	v_mfma_f32_16x16x32_bf16 v[112:115], v[190:193], v[204:207], v[112:115]
	v_mfma_f32_16x16x32_bf16 v[100:103], v[182:185], v[212:215], v[100:103]
	v_mfma_f32_16x16x32_bf16 v[96:99], v[190:193], v[212:215], v[96:99]
	v_mfma_f32_16x16x32_bf16 v[84:87], v[182:185], v[220:223], v[84:87]
	v_mfma_f32_16x16x32_bf16 v[80:83], v[190:193], v[220:223], v[80:83]
	v_mfma_f32_16x16x32_bf16 v[68:71], v[182:185], v[228:231], v[68:71]
	v_mfma_f32_16x16x32_bf16 v[64:67], v[190:193], v[228:231], v[64:67]
	s_setprio 0
	s_barrier
	s_add_i32 s10, s12, s39
	v_lshl_add_u64 v[194:195], s[54:55], 0, v[132:133]
	s_mov_b32 m0, s10
	ds_read_b128 v[200:203], v161 offset:16384
	ds_read_b128 v[204:207], v161 offset:17408
	ds_read_b128 v[208:211], v161 offset:18432
	ds_read_b128 v[212:215], v161 offset:19456
	ds_read_b128 v[216:219], v161 offset:20480
	ds_read_b128 v[220:223], v161 offset:21504
	ds_read_b128 v[224:227], v161 offset:22528
	ds_read_b128 v[228:231], v161 offset:23552
	global_load_lds_dwordx4 v[194:195], off
	s_add_i32 m0, s10, 0x2000
	s_add_u32 s70, s54, 0x40000
	v_lshl_add_u64 v[240:241], s[54:55], 0, v[128:129]
	s_addc_u32 s71, s55, 0
	s_add_i32 s8, s8, s39
	global_load_lds_dwordx4 v[240:241], off
	v_lshl_add_u64 v[242:243], s[70:71], 0, v[132:133]
	s_mov_b32 m0, s8
	v_lshl_add_u64 v[244:245], s[56:57], 0, v[130:131]
	global_load_lds_dwordx4 v[242:243], off
	v_lshl_add_u64 v[242:243], s[70:71], 0, v[128:129]
	s_add_i32 m0, s8, 0x2000
	s_nop 0
	global_load_lds_dwordx4 v[242:243], off
	v_lshl_add_u64 v[242:243], s[56:57], 0, v[134:135]
	s_mov_b32 m0, s58
	s_nop 0
	global_load_lds_dwordx4 v[242:243], off
	s_mov_b32 m0, s59
	s_nop 0
	global_load_lds_dwordx4 v[244:245], off
	s_waitcnt vmcnt(10)
	s_waitcnt lgkmcnt(0)
	s_barrier
	s_setprio 1
	s_waitcnt lgkmcnt(0)
	v_mfma_f32_16x16x32_bf16 v[60:63], v[162:165], v[200:203], 0
	v_mfma_f32_16x16x32_bf16 v[56:59], v[170:173], v[200:203], 0
	v_mfma_f32_16x16x32_bf16 v[44:47], v[162:165], v[208:211], 0
	v_mfma_f32_16x16x32_bf16 v[40:43], v[170:173], v[208:211], 0
	v_mfma_f32_16x16x32_bf16 v[28:31], v[162:165], v[216:219], 0
	v_mfma_f32_16x16x32_bf16 v[24:27], v[170:173], v[216:219], 0
	v_mfma_f32_16x16x32_bf16 v[12:15], v[162:165], v[224:227], 0
	v_mfma_f32_16x16x32_bf16 v[8:11], v[170:173], v[224:227], 0
	v_mfma_f32_16x16x32_bf16 v[60:63], v[166:169], v[204:207], v[60:63]
	v_mfma_f32_16x16x32_bf16 v[56:59], v[174:177], v[204:207], v[56:59]
	v_mfma_f32_16x16x32_bf16 v[44:47], v[166:169], v[212:215], v[44:47]
	v_mfma_f32_16x16x32_bf16 v[40:43], v[174:177], v[212:215], v[40:43]
	v_mfma_f32_16x16x32_bf16 v[28:31], v[166:169], v[220:223], v[28:31]
	v_mfma_f32_16x16x32_bf16 v[24:27], v[174:177], v[220:223], v[24:27]
	v_mfma_f32_16x16x32_bf16 v[12:15], v[166:169], v[228:231], v[12:15]
	v_mfma_f32_16x16x32_bf16 v[8:11], v[174:177], v[228:231], v[8:11]
	s_setprio 0
	s_setprio 1
	v_mfma_f32_16x16x32_bf16 v[52:55], v[178:181], v[200:203], 0
	v_mfma_f32_16x16x32_bf16 v[48:51], v[186:189], v[200:203], 0
	v_mfma_f32_16x16x32_bf16 v[36:39], v[178:181], v[208:211], 0
	v_mfma_f32_16x16x32_bf16 v[32:35], v[186:189], v[208:211], 0
	v_mfma_f32_16x16x32_bf16 v[20:23], v[178:181], v[216:219], 0
	v_mfma_f32_16x16x32_bf16 v[16:19], v[186:189], v[216:219], 0
	v_mfma_f32_16x16x32_bf16 v[4:7], v[178:181], v[224:227], 0
	v_mfma_f32_16x16x32_bf16 v[0:3], v[186:189], v[224:227], 0
	v_mfma_f32_16x16x32_bf16 v[52:55], v[182:185], v[204:207], v[52:55]
	v_mfma_f32_16x16x32_bf16 v[48:51], v[190:193], v[204:207], v[48:51]
	v_mfma_f32_16x16x32_bf16 v[36:39], v[182:185], v[212:215], v[36:39]
	v_mfma_f32_16x16x32_bf16 v[32:35], v[190:193], v[212:215], v[32:35]
	v_mfma_f32_16x16x32_bf16 v[20:23], v[182:185], v[220:223], v[20:23]
	v_mfma_f32_16x16x32_bf16 v[16:19], v[190:193], v[220:223], v[16:19]
	v_mfma_f32_16x16x32_bf16 v[4:7], v[182:185], v[228:231], v[4:7]
	v_mfma_f32_16x16x32_bf16 v[0:3], v[190:193], v[228:231], v[0:3]
	s_setprio 0
	s_barrier
	s_branch .Lmid_g1e
